# sparse-attention window branch: interior (unmasked) key tiles take a mask-free copy of the softmax+PV step; bit-identical
# speedup vs baseline: 1.0251x; 1.0078x over previous
; DI int crow(int i, int h) { return (i & 3) + 8 * (i >> 2) + 4 * h; }
; DI float shx32(float v) { return __shfl_xor(v, 32); }
; template <bool MASKED>
; DI float online_softmax_t(f32x16 (&Sx)[2], unsigned vb, float& m, float& l) {
;   float mx = NEG;
; #pragma unroll
;   for (int mt = 0; mt < 2; ++mt)
; #pragma unroll
;     for (int i = 0; i < 16; ++i) {
;       float s = Sx[mt][i];
;       if (MASKED) { s = ((vb >> (mt * 16 + i)) & 1u) ? s : NEG; Sx[mt][i] = s; }
;       mx = fmaxf(mx, s);
;     }
;   mx = fmaxf(mx, shx32(mx));
;   const float mn = fmaxf(m, mx);
;   const float alpha = __builtin_amdgcn_exp2f((m - mn) * L2E);
;   const float mb = mn * L2E;
;   f32x2 sum2 = {0.f, 0.f};
;   const f32x2 l2e2 = {L2E, L2E}, mb2 = {mb, mb};
; #pragma unroll
;   for (int mt = 0; mt < 2; ++mt)
; #pragma unroll
;     for (int i = 0; i < 16; i += 2) {
;       const f32x2 t = (f32x2){Sx[mt][i], Sx[mt][i + 1]} * l2e2 - mb2;
;       f32x2 p = {__builtin_amdgcn_exp2f(t.x), __builtin_amdgcn_exp2f(t.y)};
;       if (MASKED) { p.x = ((vb >> (mt * 16 + i)) & 1u) ? p.x : 0.f; p.y = ((vb >> (mt * 16 + i + 1)) & 1u) ? p.y : 0.f; }
;       Sx[mt][i] = p.x; Sx[mt][i + 1] = p.y;
;       sum2 += p;
;     }
;   l = l * alpha + (sum2.x + sum2.y);
;   m = mn;
;   return alpha;
; }
; DI void nsa_item(const Params& p_, const EvenBufs& eb_, int b, int g, int tt, unsigned char* smem) {
;     ...
;     for (int kt = kt_lo; kt <= kt_hi; ++kt) {
;       __syncthreads();
;       tstore72(kr, sK, tid); tstore68(vr, sV, tid);
;       __syncthreads();
;       if (kt < kt_hi) { tload(kr, Kg + (size_t)(kt + 1) * 64 * 64, 64, tid); tload(vr, VTg + (kt + 1) * 64, SP, tid); }
;       f32x16 Sx[2]; qk_tile(sK, qf, Sx, r, h);
;       const bool masked = !((kt * 64 + 63 <= t0) && (kt * 64 > t0 + 31 - 512));
;       unsigned vb = 0;
;       if (masked) {
; #pragma unroll
;         for (int mt = 0; mt < 2; ++mt)
; #pragma unroll
;           for (int i = 0; i < 16; ++i) {
;             const int key = kt * 64 + mt * 32 + crow(i, h);
;             vb |= (unsigned)((key <= t) && (key > t - 512)) << (mt * 16 + i);
;           }
;       }
;       if (!masked) vb = 0xffffffffu;
;       const float alpha = online_softmax_t<true>(Sx, vb, m, l);
;       scale_o<2>(O, alpha);
;       pv_tile<2>(sV, Sx, O, r, h);
;     }
.Lwin_fast:
	s_nop 7
	s_add_i32 s64, s64, 1
	v_mov_b32_e32 v190, v114
	s_add_i32 s80, s80, 64
	s_nop 0
	v_mov_b32_e32 v191, v115
	v_max3_f32 v114, v190, s92, v191
	v_mov_b32_e32 v192, v116
	v_mov_b32_e32 v193, v117
	v_max3_f32 v114, v114, v192, v193
	v_mov_b32_e32 v194, v118
	v_mov_b32_e32 v195, v119
	v_max3_f32 v114, v114, v194, v195
	v_mov_b32_e32 v196, v120
	v_mov_b32_e32 v197, v121
	v_max3_f32 v114, v114, v196, v197
	v_mov_b32_e32 v198, v122
	v_mov_b32_e32 v199, v123
	v_max3_f32 v114, v114, v198, v199
	v_mov_b32_e32 v200, v124
	v_mov_b32_e32 v201, v125
	v_max3_f32 v114, v114, v200, v201
	v_mov_b32_e32 v202, v126
	v_mov_b32_e32 v203, v127
	v_max3_f32 v114, v114, v202, v203
	v_mov_b32_e32 v204, v128
	v_mov_b32_e32 v205, v129
	v_max3_f32 v116, v114, v204, v205
	s_nop 1
	v_mov_b32_e32 v114, v98
	s_nop 1
	v_mov_b32_e32 v115, v99
	v_max3_f32 v98, v116, v114, v115
	v_mov_b32_e32 v116, v100
	v_mov_b32_e32 v117, v101
	v_max3_f32 v98, v98, v116, v117
	v_mov_b32_e32 v120, v102
	v_mov_b32_e32 v121, v103
	v_max3_f32 v98, v98, v120, v121
	v_mov_b32_e32 v124, v104
	v_mov_b32_e32 v125, v105
	v_max3_f32 v98, v98, v124, v125
	v_mov_b32_e32 v104, v106
	v_mov_b32_e32 v105, v107
	v_max3_f32 v98, v98, v104, v105
	v_mov_b32_e32 v106, v108
	v_mov_b32_e32 v107, v109
	v_max3_f32 v98, v98, v106, v107
	v_mov_b32_e32 v108, v110
	v_mov_b32_e32 v109, v111
	v_max3_f32 v98, v98, v108, v109
	v_mov_b32_e32 v111, v113
	v_mov_b32_e32 v110, v112
	v_max3_f32 v32, v98, v110, v111
	ds_bpermute_b32 v98, v169, v32
	s_waitcnt lgkmcnt(0)
	v_max3_f32 v187, v189, v32, v98
	v_mul_f32_e32 v32, 0x3fb8aa3b, v187
	v_pk_fma_f32 v[100:101], v[192:193], s[96:97], v[32:33] op_sel_hi:[1,0,0] neg_lo:[0,0,1] neg_hi:[0,0,1]
	v_pk_fma_f32 v[98:99], v[190:191], s[96:97], v[32:33] op_sel_hi:[1,0,0] neg_lo:[0,0,1] neg_hi:[0,0,1]
	v_exp_f32_e32 v100, v100
	v_exp_f32_e32 v101, v101
	v_exp_f32_e32 v98, v98
	v_exp_f32_e32 v99, v99
	v_mov_b32_e32 v122, v100
	v_mov_b32_e32 v123, v101
	v_pk_fma_f32 v[100:101], v[194:195], s[96:97], v[32:33] op_sel_hi:[1,0,0] neg_lo:[0,0,1] neg_hi:[0,0,1]
	v_mov_b32_e32 v118, v98
	v_exp_f32_e32 v100, v100
	v_exp_f32_e32 v101, v101
	v_mov_b32_e32 v119, v99
	v_pk_add_f32 v[98:99], v[118:119], 0 op_sel_hi:[1,0]
	v_mov_b32_e32 v126, v100
	v_mov_b32_e32 v127, v101
	v_pk_fma_f32 v[100:101], v[196:197], s[96:97], v[32:33] op_sel_hi:[1,0,0] neg_lo:[0,0,1] neg_hi:[0,0,1]
	v_pk_add_f32 v[98:99], v[122:123], v[98:99]
	v_exp_f32_e32 v100, v100
	v_exp_f32_e32 v101, v101
	v_pk_add_f32 v[98:99], v[126:127], v[98:99]
	v_pk_fma_f32 v[110:111], v[110:111], s[96:97], v[32:33] op_sel_hi:[1,0,0] neg_lo:[0,0,1] neg_hi:[0,0,1]
	v_mov_b32_e32 v128, v100
	v_mov_b32_e32 v129, v101
	v_pk_add_f32 v[100:101], v[128:129], v[98:99]
	v_pk_fma_f32 v[98:99], v[198:199], s[96:97], v[32:33] op_sel_hi:[1,0,0] neg_lo:[0,0,1] neg_hi:[0,0,1]
	v_pk_fma_f32 v[114:115], v[114:115], s[96:97], v[32:33] op_sel_hi:[1,0,0] neg_lo:[0,0,1] neg_hi:[0,0,1]
	v_exp_f32_e32 v98, v98
	v_exp_f32_e32 v99, v99
	v_pk_fma_f32 v[116:117], v[116:117], s[96:97], v[32:33] op_sel_hi:[1,0,0] neg_lo:[0,0,1] neg_hi:[0,0,1]
	v_pk_fma_f32 v[120:121], v[120:121], s[96:97], v[32:33] op_sel_hi:[1,0,0] neg_lo:[0,0,1] neg_hi:[0,0,1]
	v_pk_add_f32 v[102:103], v[98:99], v[100:101]
	v_pk_fma_f32 v[100:101], v[200:201], s[96:97], v[32:33] op_sel_hi:[1,0,0] neg_lo:[0,0,1] neg_hi:[0,0,1]
	v_pk_fma_f32 v[124:125], v[124:125], s[96:97], v[32:33] op_sel_hi:[1,0,0] neg_lo:[0,0,1] neg_hi:[0,0,1]
	v_exp_f32_e32 v100, v100
	v_exp_f32_e32 v101, v101
	v_pk_fma_f32 v[104:105], v[104:105], s[96:97], v[32:33] op_sel_hi:[1,0,0] neg_lo:[0,0,1] neg_hi:[0,0,1]
	v_pk_fma_f32 v[106:107], v[106:107], s[96:97], v[32:33] op_sel_hi:[1,0,0] neg_lo:[0,0,1] neg_hi:[0,0,1]
	v_pk_add_f32 v[112:113], v[100:101], v[102:103]
	v_pk_fma_f32 v[102:103], v[202:203], s[96:97], v[32:33] op_sel_hi:[1,0,0] neg_lo:[0,0,1] neg_hi:[0,0,1]
	v_pk_fma_f32 v[108:109], v[108:109], s[96:97], v[32:33] op_sel_hi:[1,0,0] neg_lo:[0,0,1] neg_hi:[0,0,1]
	v_exp_f32_e32 v102, v102
	v_exp_f32_e32 v103, v103
	v_cvt_pk_bf16_f32 v194, v126, v127
	v_cvt_pk_bf16_f32 v195, v128, v129
	v_pk_add_f32 v[190:191], v[102:103], v[112:113]
	v_pk_fma_f32 v[112:113], v[204:205], s[96:97], v[32:33] op_sel_hi:[1,0,0] neg_lo:[0,0,1] neg_hi:[0,0,1]
	v_exp_f32_e32 v32, v110
	ds_read2_b64 v[126:129], v182 offset0:128 offset1:130
	ds_read2_b64 v[196:199], v182 offset0:132 offset1:134
	v_cvt_pk_bf16_f32 v192, v118, v119
	v_cvt_pk_bf16_f32 v193, v122, v123
	v_mov_b32_e32 v110, v32
	v_sub_f32_e32 v32, v189, v187
	v_mul_f32_e32 v32, 0x3fb8aa3b, v32
	v_exp_f32_e32 v32, v32
	v_exp_f32_e32 v112, v112
	v_exp_f32_e32 v113, v113
	v_exp_f32_e32 v114, v114
	v_pk_mul_f32 v[82:83], v[82:83], v[32:33] op_sel_hi:[1,0]
	v_pk_mul_f32 v[84:85], v[84:85], v[32:33] op_sel_hi:[1,0]
	v_pk_mul_f32 v[86:87], v[86:87], v[32:33] op_sel_hi:[1,0]
	v_pk_mul_f32 v[88:89], v[88:89], v[32:33] op_sel_hi:[1,0]
	v_pk_mul_f32 v[90:91], v[90:91], v[32:33] op_sel_hi:[1,0]
	v_pk_mul_f32 v[92:93], v[92:93], v[32:33] op_sel_hi:[1,0]
	v_pk_mul_f32 v[94:95], v[94:95], v[32:33] op_sel_hi:[1,0]
	v_pk_mul_f32 v[96:97], v[96:97], v[32:33] op_sel_hi:[1,0]
	v_pk_mul_f32 v[66:67], v[66:67], v[32:33] op_sel_hi:[1,0]
	v_pk_mul_f32 v[68:69], v[68:69], v[32:33] op_sel_hi:[1,0]
	s_waitcnt lgkmcnt(1)
; DI unsigned pack2(float a, float b) { bf2_t v = __builtin_convertvector((f32x2){a, b}, bf2_t); return __builtin_bit_cast(unsigned, v); }
; #define MFMA(a, b, c) __builtin_amdgcn_mfma_f32_32x32x16_bf16((a), (b), (c), 0, 0, 0)
; template <int NDT> DI void pv_tile(const bf16_t* sV, const f32x16 (&P)[2], f32x16 (&O)[NDT], int r, int h) {
; #pragma unroll
;   for (int mt = 0; mt < 2; ++mt)
; #pragma unroll
;     for (int sp = 0; sp < 2; ++sp) {
;       u32x4 pk;
;       pk.x = pack2(P[mt][8 * sp + 0], P[mt][8 * sp + 1]); pk.y = pack2(P[mt][8 * sp + 2], P[mt][8 * sp + 3]);
;       pk.z = pack2(P[mt][8 * sp + 4], P[mt][8 * sp + 5]); pk.w = pack2(P[mt][8 * sp + 6], P[mt][8 * sp + 7]);
;       const bf16x8 pb = __builtin_bit_cast(bf16x8, pk);
; #pragma unroll
;       for (int dt = 0; dt < NDT; ++dt) {
;         const bf16_t* vp = sV + (dt * 32 + r) * 68 + mt * 32 + sp * 16 + 4 * h;
;         const bf16x4 lo = *(const bf16x4*)vp, hi = *(const bf16x4*)(vp + 8);
;         const bf16x8 va = __builtin_shufflevector(lo, hi, 0, 1, 2, 3, 4, 5, 6, 7);
;         O[dt] = MFMA(va, pb, O[dt]);
;       }
;       if (NDT > 2) __builtin_amdgcn_sched_barrier(0);
;     }
; }
; DI void nsa_item(const Params& p_, const EvenBufs& eb_, int b, int g, int tt, unsigned char* smem) {
;     ...
;       const float alpha = online_softmax_t<true>(Sx, vb, m, l);
;       scale_o<2>(O, alpha);
;       pv_tile<2>(sV, Sx, O, r, h);
;     }
	v_mfma_f32_32x32x16_bf16 v[82:97], v[126:129], v[192:195], v[82:97]
	ds_read2_b64 v[126:129], v183 offset0:160 offset1:162
	v_mul_f32_e64 v70, v70, v32
	v_mul_f32_e64 v71, v71, v32
	v_mul_f32_e64 v72, v72, v32
	v_mul_f32_e64 v73, v73, v32
	v_pk_mul_f32 v[74:75], v[74:75], v[32:33] op_sel_hi:[1,0]
	v_pk_mul_f32 v[76:77], v[76:77], v[32:33] op_sel_hi:[1,0]
	v_pk_mul_f32 v[78:79], v[78:79], v[32:33] op_sel_hi:[1,0]
	v_pk_mul_f32 v[80:81], v[80:81], v[32:33] op_sel_hi:[1,0]
	v_exp_f32_e32 v115, v115
	s_waitcnt lgkmcnt(0)
	v_mfma_f32_32x32x16_bf16 v[66:81], v[126:129], v[192:195], v[66:81]
	ds_read2_b64 v[126:129], v183 offset0:164 offset1:166
	v_add_f32_e64 v190, v112, v190
	v_add_f32_e64 v191, v113, v191
	v_cvt_pk_bf16_f32 v98, v98, v99
	v_cvt_pk_bf16_f32 v99, v100, v101
	v_cvt_pk_bf16_f32 v100, v102, v103
	v_cvt_pk_bf16_f32 v101, v112, v113
	v_pk_add_f32 v[190:191], v[114:115], v[190:191]
	v_exp_f32_e32 v116, v116
	v_mfma_f32_32x32x16_bf16 v[82:97], v[196:199], v[98:101], v[82:97]
	v_exp_f32_e32 v117, v117
	v_exp_f32_e32 v120, v120
	v_exp_f32_e32 v121, v121
	v_exp_f32_e32 v124, v124
	v_exp_f32_e32 v125, v125
	s_waitcnt lgkmcnt(0)
	v_mfma_f32_32x32x16_bf16 v[66:81], v[126:129], v[98:101], v[66:81]
	v_cvt_pk_bf16_f32 v98, v114, v115
	ds_read2_b64 v[112:115], v182 offset0:136 offset1:138
	v_cvt_pk_bf16_f32 v99, v116, v117
	v_cvt_pk_bf16_f32 v100, v120, v121
	v_cvt_pk_bf16_f32 v101, v124, v125
	v_exp_f32_e32 v104, v104
	v_exp_f32_e32 v105, v105
	s_waitcnt lgkmcnt(0)
	v_mfma_f32_32x32x16_bf16 v[82:97], v[112:115], v[98:101], v[82:97]
	ds_read2_b64 v[112:115], v183 offset0:168 offset1:170
	v_add_f32_e64 v190, v116, v190
	v_add_f32_e64 v191, v117, v191
	v_add_f32_e64 v190, v120, v190
	v_add_f32_e64 v191, v121, v191
	v_pk_add_f32 v[190:191], v[124:125], v[190:191]
	v_exp_f32_e32 v106, v106
	v_pk_add_f32 v[190:191], v[104:105], v[190:191]
	s_waitcnt lgkmcnt(0)
	v_mfma_f32_32x32x16_bf16 v[66:81], v[112:115], v[98:101], v[66:81]
	v_cvt_pk_bf16_f32 v98, v104, v105
	ds_read2_b64 v[102:105], v182 offset0:140 offset1:142
	v_exp_f32_e32 v107, v107
	v_exp_f32_e32 v108, v108
	v_exp_f32_e32 v109, v109
	v_exp_f32_e32 v111, v111
	v_cvt_pk_bf16_f32 v99, v106, v107
	v_cvt_pk_bf16_f32 v100, v108, v109
	v_cvt_pk_bf16_f32 v101, v110, v111
	v_pk_add_f32 v[190:191], v[106:107], v[190:191]
	s_mov_b64 s[0:1], 0x2000
	s_waitcnt lgkmcnt(0)
	v_mfma_f32_32x32x16_bf16 v[82:97], v[102:105], v[98:101], v[82:97]
	ds_read2_b64 v[102:105], v183 offset0:172 offset1:174
	v_add_f32_e64 v190, v108, v190
	v_add_f32_e64 v191, v109, v191
	v_lshl_add_u64 v[176:177], v[176:177], 0, s[0:1]
	v_add_f32_e64 v190, v110, v190
	v_add_f32_e64 v191, v111, v191
	s_andn2_b64 vcc, exec, s[66:67]
	v_add_f32_e32 v190, v190, v191
	v_fmac_f32_e32 v190, v188, v32
	s_waitcnt lgkmcnt(0)
	v_mfma_f32_32x32x16_bf16 v[66:81], v[102:105], v[98:101], v[66:81]
	s_cbranch_vccz .LBB0_1056
	v_mov_b32_e32 v189, v187
	v_mov_b32_e32 v188, v190
	s_branch .LBB0_1083
